# attention: one static s_setprio 1 for the younger half (waves 4-7) for the whole phase, reset at phase end; later K-loops padded back to their placement; on top of P4 split + carry move + 35/33 re-dea
# speedup vs baseline: 1.0035x; 1.0035x over previous
; #define RUN(bit, ...) do { __VA_ARGS__ if (DUP_MASK & (bit)) { __syncthreads(); __VA_ARGS__ } } while (0)
;   AttnUnit u;
;   for(int i=0;S.next(i,u);++i){ S.a_ready(u); attn_unit<THRL>(u.bh/NHEAD,u.bh%NHEAD,u.qb,T.Q,T.K,T.V,T.O,lds); S.done(u); }
; __global__ void __launch_bounds__(NWAVES * 64) fwd_megakernel(Args args) {
;     ...
;         RUN(4, PH_BEGIN
;           const attn_body::AttnTensors AT{(const attn_body::bf16*)WSB(WS_QP), (const attn_body::bf16*)WSB(WS_KP), (const attn_body::bf16*)(WSB(WS_PROJ) + C_DV), (attn_body::bf16*)WSB(WS_OP)};
;           const attn_body::StaticOrder S(G, bx); attn_body::attn_phase<attn_body::StaticOrder>((char*)lds_raw, AT, S);
.LBB0_543:
	s_waitcnt lgkmcnt(0)
	v_readfirstlane_b32 s3, v216
	s_nop 3
	s_cmp_lt_u32 s3, 0x100
	s_cbranch_scc1 .Lap_done
	s_setprio 1
.Lap_done:
	s_add_u32 s23, s4, 0x17800000
	s_addc_u32 s24, s5, 0
	s_add_u32 s25, s4, 0x19800000
	s_addc_u32 s26, s5, 0
	s_add_u32 s27, s4, 0xd800a00
	s_addc_u32 s28, s5, 0
	s_add_u32 s29, s4, 0x1d800000
	s_addc_u32 s33, s5, 0
	s_cmpk_lg_i32 s2, 0x100
	s_cselect_b64 s[8:9], -1, 0
	s_and_b32 s59, s22, 3
	s_ashr_i32 s60, s22, 2
	s_xor_b32 s61, s59, 7
	s_or_b32 s62, s59, 8
	s_xor_b32 s63, s59, 15
	s_mov_b32 s70, 0
	s_branch .LBB0_546

; __device__ __forceinline__ unsigned xb_add(unsigned* p, unsigned v) { return __hip_atomic_fetch_add(p, v, __ATOMIC_RELAXED, __HIP_MEMORY_SCOPE_AGENT); }
; __device__ __forceinline__ void xcd_barrier(const XcdBarrier& b) {
;     asm volatile("s_waitcnt vmcnt(0)" ::: "memory");
;     __syncthreads();
;     if (threadIdx.x == 0) {
;         unsigned* bar = b.bar;
;         __builtin_amdgcn_s_waitcnt(0);
;         unsigned nloc = b.st[0], nx = b.st[1];
;         if (nloc == 0u) { xcd_barrier_complete(bar, b.x, nloc, nx); b.st[0] = nloc; b.st[1] = nx; }
;         const unsigned old = xb_add(&bar[XB_XSUB(b.x)], 1u);
;         const unsigned gen = old / nloc;
.LBB0_633:
	s_setprio 0
	s_nop 0
	s_nop 0
	s_nop 0
	s_nop 0
	s_nop 0
	s_nop 0
	s_nop 0
	s_nop 0
	s_nop 0
	s_nop 0
	s_nop 0
	s_nop 0
	s_nop 0
	s_nop 0
	s_nop 0
	s_nop 0
	s_nop 0
	s_nop 0
	s_nop 0
	s_nop 0
	s_nop 0
	s_nop 0
	s_nop 0
	s_nop 0
	s_nop 0
	s_mov_b64 s[6:7], s[0:1]
	s_getreg_b32 s2, hwreg(HW_REG_XCC_ID, 0, 4)
	s_waitcnt vmcnt(0)
	s_barrier
	s_mov_b64 s[4:5], exec
	v_readlane_b32 s8, v255, 0
	v_readlane_b32 s9, v255, 1
	s_and_b64 s[8:9], s[4:5], s[8:9]
	v_readlane_b32 s41, v255, 10
	s_movk_i32 s42, 0x1000
	s_mov_b64 s[48:49], 0x1200
	s_mov_b32 s62, 0x3c800000
	s_mov_b64 exec, s[8:9]
	s_cbranch_execz .LBB0_685
	v_readlane_b32 s3, v255, 2
	s_load_dwordx2 s[6:7], s[6:7], 0x118
	s_waitcnt vmcnt(0) expcnt(0) lgkmcnt(0)
	v_mov_b32_e32 v0, s3
	ds_read_b32 v3, v0
	v_readlane_b32 s3, v255, 3
	s_and_b32 s2, s2, 15
	s_waitcnt lgkmcnt(0)
	v_cmp_ne_u32_e32 vcc, 0, v3
	v_mov_b32_e32 v0, s3
	ds_read_b32 v0, v0
	s_cbranch_vccnz .LBB0_649
	s_add_u32 s8, s6, 0x1000
	s_addc_u32 s9, s7, 0
	s_add_u32 s10, s6, 0x1100
	s_addc_u32 s11, s7, 0
	s_add_u32 s12, s6, 0x1200
	s_addc_u32 s13, s7, 0
	s_add_u32 s14, s6, 0x1300
	s_addc_u32 s15, s7, 0
	s_mov_b32 s3, 1
	s_branch .LBB0_637
